# in-proj GEMM epilogue fully hand-written (all tile types: silu/logf/copy/sigmoid/rotary), plus hgrn pass2 changes
# speedup vs baseline: 1.0290x; 1.0236x over previous
.Lepi_ty:
	s_lshl_b32 s4, s2, 8
	s_cmp_lt_u32 s4, 0x1400
	s_cbranch_scc0 .Lepi_tB
	s_lshr_b32 s5, s4, 10
	s_lshl_b32 s5, s5, 25
	s_and_b32 s4, s4, 0x3ff
	s_mov_b32 s10, 11
	s_branch .Lepi_tD

.Lepi_tD:
	s_lshl_b32 s4, s4, 1
	s_add_u32 s5, s5, s4
	s_add_u32 s8, s90, 0x7000000
	s_addc_u32 s9, s91, 0
	s_add_u32 s8, s8, s5
	s_addc_u32 s9, s9, 0
	s_lshl_b32 s20, 16, s10
	s_mul_i32 s36, s20, 5
	s_lshl_b32 s18, s3, 8
	s_lshl_b32 s19, s1, 6
	s_add_u32 s18, s18, s19
	v_add_u32_e32 v157, s18, v131
	v_lshlrev_b32_e32 v157, s10, v157
	v_lshl_add_u32 v157, v132, 4, v157
	s_lshl_b32 s19, s0, 6
	v_add_u32_e32 v157, s19, v157
	v_mov_b32_e32 v167, v157
	s_mov_b32 s56, 0xbfb8aa3b
	s_mov_b32 s57, 0xbfb8aa3b
	s_mov_b32 s58, 1.0
	s_mov_b32 s59, 1.0
	s_cmp_eq_u32 s37, 0
	s_cbranch_scc1 .Lepi_silu
	s_cmp_eq_u32 s37, 1
	s_cbranch_scc1 .Lepi_log
	s_cmp_eq_u32 s37, 3
	s_cbranch_scc1 .Lepi_sig
	s_cmp_eq_u32 s37, 2
	s_cbranch_scc1 .Lepi_copy
	s_and_b32 s4, s3, 31
	s_lshl_b32 s4, s4, 8
	s_lshl_b32 s5, s1, 6
	s_add_u32 s4, s4, s5
	v_add_u32_e32 v166, s4, v131
	v_lshlrev_b32_e32 v166, 7, v166
	v_and_b32_e32 v139, 1, v132
	v_lshl_add_u32 v166, v139, 6, v166
	s_add_u32 s54, s90, 0x3410000
	s_addc_u32 s55, s91, 0
	v_xor_b32_e32 v167, 32, v130
	v_lshlrev_b32_e32 v167, 2, v167
	v_cmp_gt_u32_e32 vcc, 2, v132
	v_cndmask_b32_e64 v138, 1.0, -1.0, vcc
	s_mov_b32 s2, 0x3e0293ee
	s_mov_b32 s3, 0x3e0293ee
	s_cmp_lg_u32 s0, 0
	s_cbranch_scc1 .Lepi_rot_plain
	global_load_dwordx4 v[130:133], v166, s[54:55]
	global_load_dwordx4 v[134:137], v166, s[54:55] offset:16
	global_load_dwordx4 v[196:199], v166, s[54:55] offset:32
	global_load_dwordx4 v[158:161], v166, s[54:55] offset:48
	s_waitcnt vmcnt(0)
	v_mul_f32_e32 v131, v138, v131
	v_mul_f32_e32 v133, v138, v133
	v_mul_f32_e32 v135, v138, v135
	v_mul_f32_e32 v137, v138, v137
	v_mul_f32_e32 v197, v138, v197
	v_mul_f32_e32 v199, v138, v199
	v_mul_f32_e32 v159, v138, v159
	v_mul_f32_e32 v161, v138, v161
	ds_bpermute_b32 v162, v167, v126
	ds_bpermute_b32 v163, v167, v127
	ds_bpermute_b32 v164, v167, v128
	ds_bpermute_b32 v165, v167, v129
	v_mul_f32_e32 v126, v126, v130
	v_mul_f32_e32 v127, v127, v132
	v_mul_f32_e32 v128, v128, v134
	v_mul_f32_e32 v129, v129, v136
	s_waitcnt lgkmcnt(3)
	v_fmac_f32_e32 v126, v162, v131
	s_waitcnt lgkmcnt(2)
	v_fmac_f32_e32 v127, v163, v133
	s_waitcnt lgkmcnt(1)
	v_fmac_f32_e32 v128, v164, v135
	s_waitcnt lgkmcnt(0)
	v_fmac_f32_e32 v129, v165, v137
	ds_bpermute_b32 v162, v167, v122
	ds_bpermute_b32 v163, v167, v123
	ds_bpermute_b32 v164, v167, v124
	ds_bpermute_b32 v165, v167, v125
	v_mul_f32_e32 v122, v122, v196
	v_mul_f32_e32 v123, v123, v198
	v_mul_f32_e32 v124, v124, v158
	v_mul_f32_e32 v125, v125, v160
	s_waitcnt lgkmcnt(3)
	v_fmac_f32_e32 v122, v162, v197
	s_waitcnt lgkmcnt(2)
	v_fmac_f32_e32 v123, v163, v199
	s_waitcnt lgkmcnt(1)
	v_fmac_f32_e32 v124, v164, v159
	s_waitcnt lgkmcnt(0)
	v_fmac_f32_e32 v125, v165, v161
	s_cmp_lg_u32 s37, 4
	s_cbranch_scc1 .Lepi_rs_0_0
	v_pk_mul_f32 v[126:127], v[126:127], s[2:3]
	v_pk_mul_f32 v[128:129], v[128:129], s[2:3]
	v_pk_mul_f32 v[122:123], v[122:123], s[2:3]
	v_pk_mul_f32 v[124:125], v[124:125], s[2:3]
.Lepi_rs_0_0:
	v_cvt_pk_bf16_f32 v126, v126, v127
	v_cvt_pk_bf16_f32 v127, v128, v129
	v_cvt_pk_bf16_f32 v128, v122, v123
	v_cvt_pk_bf16_f32 v129, v124, v125
	global_store_dwordx4 v157, v[126:129], s[8:9]
	ds_bpermute_b32 v162, v167, v118
	ds_bpermute_b32 v163, v167, v119
	ds_bpermute_b32 v164, v167, v120
	ds_bpermute_b32 v165, v167, v121
	v_mul_f32_e32 v118, v118, v130
	v_mul_f32_e32 v119, v119, v132
	v_mul_f32_e32 v120, v120, v134
	v_mul_f32_e32 v121, v121, v136
	s_waitcnt lgkmcnt(3)
	v_fmac_f32_e32 v118, v162, v131
	s_waitcnt lgkmcnt(2)
	v_fmac_f32_e32 v119, v163, v133
	s_waitcnt lgkmcnt(1)
	v_fmac_f32_e32 v120, v164, v135
	s_waitcnt lgkmcnt(0)
	v_fmac_f32_e32 v121, v165, v137
	ds_bpermute_b32 v162, v167, v114
	ds_bpermute_b32 v163, v167, v115
	ds_bpermute_b32 v164, v167, v116
	ds_bpermute_b32 v165, v167, v117
	v_mul_f32_e32 v114, v114, v196
	v_mul_f32_e32 v115, v115, v198
	v_mul_f32_e32 v116, v116, v158
	v_mul_f32_e32 v117, v117, v160
	s_waitcnt lgkmcnt(3)
	v_fmac_f32_e32 v114, v162, v197
	s_waitcnt lgkmcnt(2)
	v_fmac_f32_e32 v115, v163, v199
	s_waitcnt lgkmcnt(1)
	v_fmac_f32_e32 v116, v164, v159
	s_waitcnt lgkmcnt(0)
	v_fmac_f32_e32 v117, v165, v161
	s_cmp_lg_u32 s37, 4
	s_cbranch_scc1 .Lepi_rs_0_1
	v_pk_mul_f32 v[118:119], v[118:119], s[2:3]
	v_pk_mul_f32 v[120:121], v[120:121], s[2:3]
	v_pk_mul_f32 v[114:115], v[114:115], s[2:3]
	v_pk_mul_f32 v[116:117], v[116:117], s[2:3]
.Lepi_rs_0_1:
	v_cvt_pk_bf16_f32 v118, v118, v119
	v_cvt_pk_bf16_f32 v119, v120, v121
	v_cvt_pk_bf16_f32 v120, v114, v115
	v_cvt_pk_bf16_f32 v121, v116, v117
	global_store_dwordx4 v157, v[118:121], s[8:9] offset:256
	s_nop 1
	v_add_u32_e32 v166, 0x800, v166
	global_load_dwordx4 v[126:129], v166, s[54:55]
	global_load_dwordx4 v[122:125], v166, s[54:55] offset:16
	global_load_dwordx4 v[118:121], v166, s[54:55] offset:32
	global_load_dwordx4 v[114:117], v166, s[54:55] offset:48
	v_add_u32_e32 v157, s20, v157
	v_add_u32_e32 v166, 0x800, v166
	global_load_dwordx4 v[130:133], v166, s[54:55]
	global_load_dwordx4 v[134:137], v166, s[54:55] offset:16
	global_load_dwordx4 v[196:199], v166, s[54:55] offset:32
	global_load_dwordx4 v[158:161], v166, s[54:55] offset:48
	s_waitcnt vmcnt(4)
	v_mul_f32_e32 v127, v138, v127
	v_mul_f32_e32 v129, v138, v129
	v_mul_f32_e32 v123, v138, v123
	v_mul_f32_e32 v125, v138, v125
	v_mul_f32_e32 v119, v138, v119
	v_mul_f32_e32 v121, v138, v121
	v_mul_f32_e32 v115, v138, v115
	v_mul_f32_e32 v117, v138, v117
	ds_bpermute_b32 v162, v167, v110
	ds_bpermute_b32 v163, v167, v111
	ds_bpermute_b32 v164, v167, v112
	ds_bpermute_b32 v165, v167, v113
	v_mul_f32_e32 v110, v110, v126
	v_mul_f32_e32 v111, v111, v128
	v_mul_f32_e32 v112, v112, v122
	v_mul_f32_e32 v113, v113, v124
	s_waitcnt lgkmcnt(3)
	v_fmac_f32_e32 v110, v162, v127
	s_waitcnt lgkmcnt(2)
	v_fmac_f32_e32 v111, v163, v129
	s_waitcnt lgkmcnt(1)
	v_fmac_f32_e32 v112, v164, v123
	s_waitcnt lgkmcnt(0)
	v_fmac_f32_e32 v113, v165, v125
	ds_bpermute_b32 v162, v167, v106
	ds_bpermute_b32 v163, v167, v107
	ds_bpermute_b32 v164, v167, v108
	ds_bpermute_b32 v165, v167, v109
	v_mul_f32_e32 v106, v106, v118
	v_mul_f32_e32 v107, v107, v120
	v_mul_f32_e32 v108, v108, v114
	v_mul_f32_e32 v109, v109, v116
	s_waitcnt lgkmcnt(3)
	v_fmac_f32_e32 v106, v162, v119
	s_waitcnt lgkmcnt(2)
	v_fmac_f32_e32 v107, v163, v121
	s_waitcnt lgkmcnt(1)
	v_fmac_f32_e32 v108, v164, v115
	s_waitcnt lgkmcnt(0)
	v_fmac_f32_e32 v109, v165, v117
	s_cmp_lg_u32 s37, 4
	s_cbranch_scc1 .Lepi_rs_1_0
	v_pk_mul_f32 v[110:111], v[110:111], s[2:3]
	v_pk_mul_f32 v[112:113], v[112:113], s[2:3]
	v_pk_mul_f32 v[106:107], v[106:107], s[2:3]
	v_pk_mul_f32 v[108:109], v[108:109], s[2:3]
.Lepi_rs_1_0:
	v_cvt_pk_bf16_f32 v110, v110, v111
	v_cvt_pk_bf16_f32 v111, v112, v113
	v_cvt_pk_bf16_f32 v112, v106, v107
	v_cvt_pk_bf16_f32 v113, v108, v109
	global_store_dwordx4 v157, v[110:113], s[8:9]
	ds_bpermute_b32 v162, v167, v102
	ds_bpermute_b32 v163, v167, v103
	ds_bpermute_b32 v164, v167, v104
	ds_bpermute_b32 v165, v167, v105
	v_mul_f32_e32 v102, v102, v126
	v_mul_f32_e32 v103, v103, v128
	v_mul_f32_e32 v104, v104, v122
	v_mul_f32_e32 v105, v105, v124
	s_waitcnt lgkmcnt(3)
	v_fmac_f32_e32 v102, v162, v127
	s_waitcnt lgkmcnt(2)
	v_fmac_f32_e32 v103, v163, v129
	s_waitcnt lgkmcnt(1)
	v_fmac_f32_e32 v104, v164, v123
	s_waitcnt lgkmcnt(0)
	v_fmac_f32_e32 v105, v165, v125
	ds_bpermute_b32 v162, v167, v98
	ds_bpermute_b32 v163, v167, v99
	ds_bpermute_b32 v164, v167, v100
	ds_bpermute_b32 v165, v167, v101
	v_mul_f32_e32 v98, v98, v118
	v_mul_f32_e32 v99, v99, v120
	v_mul_f32_e32 v100, v100, v114
	v_mul_f32_e32 v101, v101, v116
	s_waitcnt lgkmcnt(3)
	v_fmac_f32_e32 v98, v162, v119
	s_waitcnt lgkmcnt(2)
	v_fmac_f32_e32 v99, v163, v121
	s_waitcnt lgkmcnt(1)
	v_fmac_f32_e32 v100, v164, v115
	s_waitcnt lgkmcnt(0)
	v_fmac_f32_e32 v101, v165, v117
	s_cmp_lg_u32 s37, 4
	s_cbranch_scc1 .Lepi_rs_1_1
	v_pk_mul_f32 v[102:103], v[102:103], s[2:3]
	v_pk_mul_f32 v[104:105], v[104:105], s[2:3]
	v_pk_mul_f32 v[98:99], v[98:99], s[2:3]
	v_pk_mul_f32 v[100:101], v[100:101], s[2:3]
.Lepi_rs_1_1:
	v_cvt_pk_bf16_f32 v102, v102, v103
	v_cvt_pk_bf16_f32 v103, v104, v105
	v_cvt_pk_bf16_f32 v104, v98, v99
	v_cvt_pk_bf16_f32 v105, v100, v101
	global_store_dwordx4 v157, v[102:105], s[8:9] offset:256
	v_add_u32_e32 v157, s20, v157
	v_add_u32_e32 v166, 0x800, v166
	global_load_dwordx4 v[126:129], v166, s[54:55]
	global_load_dwordx4 v[122:125], v166, s[54:55] offset:16
	global_load_dwordx4 v[118:121], v166, s[54:55] offset:32
	global_load_dwordx4 v[114:117], v166, s[54:55] offset:48
	s_waitcnt vmcnt(6)
	v_mul_f32_e32 v131, v138, v131
	v_mul_f32_e32 v133, v138, v133
	v_mul_f32_e32 v135, v138, v135
	v_mul_f32_e32 v137, v138, v137
	v_mul_f32_e32 v197, v138, v197
	v_mul_f32_e32 v199, v138, v199
	v_mul_f32_e32 v159, v138, v159
	v_mul_f32_e32 v161, v138, v161
	ds_bpermute_b32 v162, v167, v94
	ds_bpermute_b32 v163, v167, v95
	ds_bpermute_b32 v164, v167, v96
	ds_bpermute_b32 v165, v167, v97
	v_mul_f32_e32 v94, v94, v130
	v_mul_f32_e32 v95, v95, v132
	v_mul_f32_e32 v96, v96, v134
	v_mul_f32_e32 v97, v97, v136
	s_waitcnt lgkmcnt(3)
	v_fmac_f32_e32 v94, v162, v131
	s_waitcnt lgkmcnt(2)
	v_fmac_f32_e32 v95, v163, v133
	s_waitcnt lgkmcnt(1)
	v_fmac_f32_e32 v96, v164, v135
	s_waitcnt lgkmcnt(0)
	v_fmac_f32_e32 v97, v165, v137
	ds_bpermute_b32 v162, v167, v90
	ds_bpermute_b32 v163, v167, v91
	ds_bpermute_b32 v164, v167, v92
	ds_bpermute_b32 v165, v167, v93
	v_mul_f32_e32 v90, v90, v196
	v_mul_f32_e32 v91, v91, v198
	v_mul_f32_e32 v92, v92, v158
	v_mul_f32_e32 v93, v93, v160
	s_waitcnt lgkmcnt(3)
	v_fmac_f32_e32 v90, v162, v197
	s_waitcnt lgkmcnt(2)
	v_fmac_f32_e32 v91, v163, v199
	s_waitcnt lgkmcnt(1)
	v_fmac_f32_e32 v92, v164, v159
	s_waitcnt lgkmcnt(0)
	v_fmac_f32_e32 v93, v165, v161
	s_cmp_lg_u32 s37, 4
	s_cbranch_scc1 .Lepi_rs_2_0
	v_pk_mul_f32 v[94:95], v[94:95], s[2:3]
	v_pk_mul_f32 v[96:97], v[96:97], s[2:3]
	v_pk_mul_f32 v[90:91], v[90:91], s[2:3]
	v_pk_mul_f32 v[92:93], v[92:93], s[2:3]
.Lepi_rs_2_0:
	v_cvt_pk_bf16_f32 v94, v94, v95
	v_cvt_pk_bf16_f32 v95, v96, v97
	v_cvt_pk_bf16_f32 v96, v90, v91
	v_cvt_pk_bf16_f32 v97, v92, v93
	global_store_dwordx4 v157, v[94:97], s[8:9]
	ds_bpermute_b32 v162, v167, v86
	ds_bpermute_b32 v163, v167, v87
	ds_bpermute_b32 v164, v167, v88
	ds_bpermute_b32 v165, v167, v89
	v_mul_f32_e32 v86, v86, v130
	v_mul_f32_e32 v87, v87, v132
	v_mul_f32_e32 v88, v88, v134
	v_mul_f32_e32 v89, v89, v136
	s_waitcnt lgkmcnt(3)
	v_fmac_f32_e32 v86, v162, v131
	s_waitcnt lgkmcnt(2)
	v_fmac_f32_e32 v87, v163, v133
	s_waitcnt lgkmcnt(1)
	v_fmac_f32_e32 v88, v164, v135
	s_waitcnt lgkmcnt(0)
	v_fmac_f32_e32 v89, v165, v137
	ds_bpermute_b32 v162, v167, v82
	ds_bpermute_b32 v163, v167, v83
	ds_bpermute_b32 v164, v167, v84
	ds_bpermute_b32 v165, v167, v85
	v_mul_f32_e32 v82, v82, v196
	v_mul_f32_e32 v83, v83, v198
	v_mul_f32_e32 v84, v84, v158
	v_mul_f32_e32 v85, v85, v160
	s_waitcnt lgkmcnt(3)
	v_fmac_f32_e32 v82, v162, v197
	s_waitcnt lgkmcnt(2)
	v_fmac_f32_e32 v83, v163, v199
	s_waitcnt lgkmcnt(1)
	v_fmac_f32_e32 v84, v164, v159
	s_waitcnt lgkmcnt(0)
	v_fmac_f32_e32 v85, v165, v161
	s_cmp_lg_u32 s37, 4
	s_cbranch_scc1 .Lepi_rs_2_1
	v_pk_mul_f32 v[86:87], v[86:87], s[2:3]
	v_pk_mul_f32 v[88:89], v[88:89], s[2:3]
	v_pk_mul_f32 v[82:83], v[82:83], s[2:3]
	v_pk_mul_f32 v[84:85], v[84:85], s[2:3]
.Lepi_rs_2_1:
	v_cvt_pk_bf16_f32 v86, v86, v87
	v_cvt_pk_bf16_f32 v87, v88, v89
	v_cvt_pk_bf16_f32 v88, v82, v83
	v_cvt_pk_bf16_f32 v89, v84, v85
	global_store_dwordx4 v157, v[86:89], s[8:9] offset:256
	v_add_u32_e32 v157, s20, v157
	v_add_u32_e32 v166, 0x2800, v166
	global_load_dwordx4 v[130:133], v166, s[54:55]
	global_load_dwordx4 v[134:137], v166, s[54:55] offset:16
	global_load_dwordx4 v[196:199], v166, s[54:55] offset:32
	global_load_dwordx4 v[158:161], v166, s[54:55] offset:48
	s_waitcnt vmcnt(6)
	v_mul_f32_e32 v127, v138, v127
	v_mul_f32_e32 v129, v138, v129
	v_mul_f32_e32 v123, v138, v123
	v_mul_f32_e32 v125, v138, v125
	v_mul_f32_e32 v119, v138, v119
	v_mul_f32_e32 v121, v138, v121
	v_mul_f32_e32 v115, v138, v115
	v_mul_f32_e32 v117, v138, v117
	ds_bpermute_b32 v162, v167, v78
	ds_bpermute_b32 v163, v167, v79
	ds_bpermute_b32 v164, v167, v80
	ds_bpermute_b32 v165, v167, v81
	v_mul_f32_e32 v78, v78, v126
	v_mul_f32_e32 v79, v79, v128
	v_mul_f32_e32 v80, v80, v122
	v_mul_f32_e32 v81, v81, v124
	s_waitcnt lgkmcnt(3)
	v_fmac_f32_e32 v78, v162, v127
	s_waitcnt lgkmcnt(2)
	v_fmac_f32_e32 v79, v163, v129
	s_waitcnt lgkmcnt(1)
	v_fmac_f32_e32 v80, v164, v123
	s_waitcnt lgkmcnt(0)
	v_fmac_f32_e32 v81, v165, v125
	ds_bpermute_b32 v162, v167, v74
	ds_bpermute_b32 v163, v167, v75
	ds_bpermute_b32 v164, v167, v76
	ds_bpermute_b32 v165, v167, v77
	v_mul_f32_e32 v74, v74, v118
	v_mul_f32_e32 v75, v75, v120
	v_mul_f32_e32 v76, v76, v114
	v_mul_f32_e32 v77, v77, v116
	s_waitcnt lgkmcnt(3)
	v_fmac_f32_e32 v74, v162, v119
	s_waitcnt lgkmcnt(2)
	v_fmac_f32_e32 v75, v163, v121
	s_waitcnt lgkmcnt(1)
	v_fmac_f32_e32 v76, v164, v115
	s_waitcnt lgkmcnt(0)
	v_fmac_f32_e32 v77, v165, v117
	s_cmp_lg_u32 s37, 4
	s_cbranch_scc1 .Lepi_rs_3_0
	v_pk_mul_f32 v[78:79], v[78:79], s[2:3]
	v_pk_mul_f32 v[80:81], v[80:81], s[2:3]
	v_pk_mul_f32 v[74:75], v[74:75], s[2:3]
	v_pk_mul_f32 v[76:77], v[76:77], s[2:3]
.Lepi_rs_3_0:
	v_cvt_pk_bf16_f32 v78, v78, v79
	v_cvt_pk_bf16_f32 v79, v80, v81
	v_cvt_pk_bf16_f32 v80, v74, v75
	v_cvt_pk_bf16_f32 v81, v76, v77
	global_store_dwordx4 v157, v[78:81], s[8:9]
	ds_bpermute_b32 v162, v167, v70
	ds_bpermute_b32 v163, v167, v71
	ds_bpermute_b32 v164, v167, v72
	ds_bpermute_b32 v165, v167, v73
	v_mul_f32_e32 v70, v70, v126
	v_mul_f32_e32 v71, v71, v128
	v_mul_f32_e32 v72, v72, v122
	v_mul_f32_e32 v73, v73, v124
	s_waitcnt lgkmcnt(3)
	v_fmac_f32_e32 v70, v162, v127
	s_waitcnt lgkmcnt(2)
	v_fmac_f32_e32 v71, v163, v129
	s_waitcnt lgkmcnt(1)
	v_fmac_f32_e32 v72, v164, v123
	s_waitcnt lgkmcnt(0)
	v_fmac_f32_e32 v73, v165, v125
	ds_bpermute_b32 v162, v167, v66
	ds_bpermute_b32 v163, v167, v67
	ds_bpermute_b32 v164, v167, v68
	ds_bpermute_b32 v165, v167, v69
	v_mul_f32_e32 v66, v66, v118
	v_mul_f32_e32 v67, v67, v120
	v_mul_f32_e32 v68, v68, v114
	v_mul_f32_e32 v69, v69, v116
	s_waitcnt lgkmcnt(3)
	v_fmac_f32_e32 v66, v162, v119
	s_waitcnt lgkmcnt(2)
	v_fmac_f32_e32 v67, v163, v121
	s_waitcnt lgkmcnt(1)
	v_fmac_f32_e32 v68, v164, v115
	s_waitcnt lgkmcnt(0)
	v_fmac_f32_e32 v69, v165, v117
	s_cmp_lg_u32 s37, 4
	s_cbranch_scc1 .Lepi_rs_3_1
	v_pk_mul_f32 v[70:71], v[70:71], s[2:3]
	v_pk_mul_f32 v[72:73], v[72:73], s[2:3]
	v_pk_mul_f32 v[66:67], v[66:67], s[2:3]
	v_pk_mul_f32 v[68:69], v[68:69], s[2:3]
.Lepi_rs_3_1:
	v_cvt_pk_bf16_f32 v70, v70, v71
	v_cvt_pk_bf16_f32 v71, v72, v73
	v_cvt_pk_bf16_f32 v72, v66, v67
	v_cvt_pk_bf16_f32 v73, v68, v69
	global_store_dwordx4 v157, v[70:73], s[8:9] offset:256
	v_add_u32_e32 v157, s36, v157
	v_add_u32_e32 v166, 0x800, v166
	global_load_dwordx4 v[126:129], v166, s[54:55]
	global_load_dwordx4 v[122:125], v166, s[54:55] offset:16
	global_load_dwordx4 v[118:121], v166, s[54:55] offset:32
	global_load_dwordx4 v[114:117], v166, s[54:55] offset:48
	s_waitcnt vmcnt(6)
	v_mul_f32_e32 v131, v138, v131
	v_mul_f32_e32 v133, v138, v133
	v_mul_f32_e32 v135, v138, v135
	v_mul_f32_e32 v137, v138, v137
	v_mul_f32_e32 v197, v138, v197
	v_mul_f32_e32 v199, v138, v199
	v_mul_f32_e32 v159, v138, v159
	v_mul_f32_e32 v161, v138, v161
	ds_bpermute_b32 v162, v167, v60
	ds_bpermute_b32 v163, v167, v61
	ds_bpermute_b32 v164, v167, v62
	ds_bpermute_b32 v165, v167, v63
	v_mul_f32_e32 v60, v60, v130
	v_mul_f32_e32 v61, v61, v132
	v_mul_f32_e32 v62, v62, v134
	v_mul_f32_e32 v63, v63, v136
	s_waitcnt lgkmcnt(3)
	v_fmac_f32_e32 v60, v162, v131
	s_waitcnt lgkmcnt(2)
	v_fmac_f32_e32 v61, v163, v133
	s_waitcnt lgkmcnt(1)
	v_fmac_f32_e32 v62, v164, v135
	s_waitcnt lgkmcnt(0)
	v_fmac_f32_e32 v63, v165, v137
	ds_bpermute_b32 v162, v167, v56
	ds_bpermute_b32 v163, v167, v57
	ds_bpermute_b32 v164, v167, v58
	ds_bpermute_b32 v165, v167, v59
	v_mul_f32_e32 v56, v56, v196
	v_mul_f32_e32 v57, v57, v198
	v_mul_f32_e32 v58, v58, v158
	v_mul_f32_e32 v59, v59, v160
	s_waitcnt lgkmcnt(3)
	v_fmac_f32_e32 v56, v162, v197
	s_waitcnt lgkmcnt(2)
	v_fmac_f32_e32 v57, v163, v199
	s_waitcnt lgkmcnt(1)
	v_fmac_f32_e32 v58, v164, v159
	s_waitcnt lgkmcnt(0)
	v_fmac_f32_e32 v59, v165, v161
	s_cmp_lg_u32 s37, 4
	s_cbranch_scc1 .Lepi_rs_4_0
	v_pk_mul_f32 v[60:61], v[60:61], s[2:3]
	v_pk_mul_f32 v[62:63], v[62:63], s[2:3]
	v_pk_mul_f32 v[56:57], v[56:57], s[2:3]
	v_pk_mul_f32 v[58:59], v[58:59], s[2:3]
.Lepi_rs_4_0:
	v_cvt_pk_bf16_f32 v60, v60, v61
	v_cvt_pk_bf16_f32 v61, v62, v63
	v_cvt_pk_bf16_f32 v62, v56, v57
	v_cvt_pk_bf16_f32 v63, v58, v59
	global_store_dwordx4 v157, v[60:63], s[8:9]
	ds_bpermute_b32 v162, v167, v52
	ds_bpermute_b32 v163, v167, v53
	ds_bpermute_b32 v164, v167, v54
	ds_bpermute_b32 v165, v167, v55
	v_mul_f32_e32 v52, v52, v130
	v_mul_f32_e32 v53, v53, v132
	v_mul_f32_e32 v54, v54, v134
	v_mul_f32_e32 v55, v55, v136
	s_waitcnt lgkmcnt(3)
	v_fmac_f32_e32 v52, v162, v131
	s_waitcnt lgkmcnt(2)
	v_fmac_f32_e32 v53, v163, v133
	s_waitcnt lgkmcnt(1)
	v_fmac_f32_e32 v54, v164, v135
	s_waitcnt lgkmcnt(0)
	v_fmac_f32_e32 v55, v165, v137
	ds_bpermute_b32 v162, v167, v48
	ds_bpermute_b32 v163, v167, v49
	ds_bpermute_b32 v164, v167, v50
	ds_bpermute_b32 v165, v167, v51
	v_mul_f32_e32 v48, v48, v196
	v_mul_f32_e32 v49, v49, v198
	v_mul_f32_e32 v50, v50, v158
	v_mul_f32_e32 v51, v51, v160
	s_waitcnt lgkmcnt(3)
	v_fmac_f32_e32 v48, v162, v197
	s_waitcnt lgkmcnt(2)
	v_fmac_f32_e32 v49, v163, v199
	s_waitcnt lgkmcnt(1)
	v_fmac_f32_e32 v50, v164, v159
	s_waitcnt lgkmcnt(0)
	v_fmac_f32_e32 v51, v165, v161
	s_cmp_lg_u32 s37, 4
	s_cbranch_scc1 .Lepi_rs_4_1
	v_pk_mul_f32 v[52:53], v[52:53], s[2:3]
	v_pk_mul_f32 v[54:55], v[54:55], s[2:3]
	v_pk_mul_f32 v[48:49], v[48:49], s[2:3]
	v_pk_mul_f32 v[50:51], v[50:51], s[2:3]
.Lepi_rs_4_1:
	v_cvt_pk_bf16_f32 v52, v52, v53
	v_cvt_pk_bf16_f32 v53, v54, v55
	v_cvt_pk_bf16_f32 v54, v48, v49
	v_cvt_pk_bf16_f32 v55, v50, v51
	global_store_dwordx4 v157, v[52:55], s[8:9] offset:256
	v_add_u32_e32 v157, s20, v157
	v_add_u32_e32 v166, 0x800, v166
	global_load_dwordx4 v[130:133], v166, s[54:55]
	global_load_dwordx4 v[134:137], v166, s[54:55] offset:16
	global_load_dwordx4 v[196:199], v166, s[54:55] offset:32
	global_load_dwordx4 v[158:161], v166, s[54:55] offset:48
	s_waitcnt vmcnt(6)
	v_mul_f32_e32 v127, v138, v127
	v_mul_f32_e32 v129, v138, v129
	v_mul_f32_e32 v123, v138, v123
	v_mul_f32_e32 v125, v138, v125
	v_mul_f32_e32 v119, v138, v119
	v_mul_f32_e32 v121, v138, v121
	v_mul_f32_e32 v115, v138, v115
	v_mul_f32_e32 v117, v138, v117
	ds_bpermute_b32 v162, v167, v44
	ds_bpermute_b32 v163, v167, v45
	ds_bpermute_b32 v164, v167, v46
	ds_bpermute_b32 v165, v167, v47
	v_mul_f32_e32 v44, v44, v126
	v_mul_f32_e32 v45, v45, v128
	v_mul_f32_e32 v46, v46, v122
	v_mul_f32_e32 v47, v47, v124
	s_waitcnt lgkmcnt(3)
	v_fmac_f32_e32 v44, v162, v127
	s_waitcnt lgkmcnt(2)
	v_fmac_f32_e32 v45, v163, v129
	s_waitcnt lgkmcnt(1)
	v_fmac_f32_e32 v46, v164, v123
	s_waitcnt lgkmcnt(0)
	v_fmac_f32_e32 v47, v165, v125
	ds_bpermute_b32 v162, v167, v40
	ds_bpermute_b32 v163, v167, v41
	ds_bpermute_b32 v164, v167, v42
	ds_bpermute_b32 v165, v167, v43
	v_mul_f32_e32 v40, v40, v118
	v_mul_f32_e32 v41, v41, v120
	v_mul_f32_e32 v42, v42, v114
	v_mul_f32_e32 v43, v43, v116
	s_waitcnt lgkmcnt(3)
	v_fmac_f32_e32 v40, v162, v119
	s_waitcnt lgkmcnt(2)
	v_fmac_f32_e32 v41, v163, v121
	s_waitcnt lgkmcnt(1)
	v_fmac_f32_e32 v42, v164, v115
	s_waitcnt lgkmcnt(0)
	v_fmac_f32_e32 v43, v165, v117
	s_cmp_lg_u32 s37, 4
	s_cbranch_scc1 .Lepi_rs_5_0
	v_pk_mul_f32 v[44:45], v[44:45], s[2:3]
	v_pk_mul_f32 v[46:47], v[46:47], s[2:3]
	v_pk_mul_f32 v[40:41], v[40:41], s[2:3]
	v_pk_mul_f32 v[42:43], v[42:43], s[2:3]
.Lepi_rs_5_0:
	v_cvt_pk_bf16_f32 v44, v44, v45
	v_cvt_pk_bf16_f32 v45, v46, v47
	v_cvt_pk_bf16_f32 v46, v40, v41
	v_cvt_pk_bf16_f32 v47, v42, v43
	global_store_dwordx4 v157, v[44:47], s[8:9]
	ds_bpermute_b32 v162, v167, v36
	ds_bpermute_b32 v163, v167, v37
	ds_bpermute_b32 v164, v167, v38
	ds_bpermute_b32 v165, v167, v39
	v_mul_f32_e32 v36, v36, v126
	v_mul_f32_e32 v37, v37, v128
	v_mul_f32_e32 v38, v38, v122
	v_mul_f32_e32 v39, v39, v124
	s_waitcnt lgkmcnt(3)
	v_fmac_f32_e32 v36, v162, v127
	s_waitcnt lgkmcnt(2)
	v_fmac_f32_e32 v37, v163, v129
	s_waitcnt lgkmcnt(1)
	v_fmac_f32_e32 v38, v164, v123
	s_waitcnt lgkmcnt(0)
	v_fmac_f32_e32 v39, v165, v125
	ds_bpermute_b32 v162, v167, v32
	ds_bpermute_b32 v163, v167, v33
	ds_bpermute_b32 v164, v167, v34
	ds_bpermute_b32 v165, v167, v35
	v_mul_f32_e32 v32, v32, v118
	v_mul_f32_e32 v33, v33, v120
	v_mul_f32_e32 v34, v34, v114
	v_mul_f32_e32 v35, v35, v116
	s_waitcnt lgkmcnt(3)
	v_fmac_f32_e32 v32, v162, v119
	s_waitcnt lgkmcnt(2)
	v_fmac_f32_e32 v33, v163, v121
	s_waitcnt lgkmcnt(1)
	v_fmac_f32_e32 v34, v164, v115
	s_waitcnt lgkmcnt(0)
	v_fmac_f32_e32 v35, v165, v117
	s_cmp_lg_u32 s37, 4
	s_cbranch_scc1 .Lepi_rs_5_1
	v_pk_mul_f32 v[36:37], v[36:37], s[2:3]
	v_pk_mul_f32 v[38:39], v[38:39], s[2:3]
	v_pk_mul_f32 v[32:33], v[32:33], s[2:3]
	v_pk_mul_f32 v[34:35], v[34:35], s[2:3]
.Lepi_rs_5_1:
	v_cvt_pk_bf16_f32 v36, v36, v37
	v_cvt_pk_bf16_f32 v37, v38, v39
	v_cvt_pk_bf16_f32 v38, v32, v33
	v_cvt_pk_bf16_f32 v39, v34, v35
	global_store_dwordx4 v157, v[36:39], s[8:9] offset:256
	v_add_u32_e32 v157, s20, v157
	v_add_u32_e32 v166, 0x800, v166
	global_load_dwordx4 v[126:129], v166, s[54:55]
	global_load_dwordx4 v[122:125], v166, s[54:55] offset:16
	global_load_dwordx4 v[118:121], v166, s[54:55] offset:32
	global_load_dwordx4 v[114:117], v166, s[54:55] offset:48
	s_waitcnt vmcnt(6)
	v_mul_f32_e32 v131, v138, v131
	v_mul_f32_e32 v133, v138, v133
	v_mul_f32_e32 v135, v138, v135
	v_mul_f32_e32 v137, v138, v137
	v_mul_f32_e32 v197, v138, v197
	v_mul_f32_e32 v199, v138, v199
	v_mul_f32_e32 v159, v138, v159
	v_mul_f32_e32 v161, v138, v161
	ds_bpermute_b32 v162, v167, v28
	ds_bpermute_b32 v163, v167, v29
	ds_bpermute_b32 v164, v167, v30
	ds_bpermute_b32 v165, v167, v31
	v_mul_f32_e32 v28, v28, v130
	v_mul_f32_e32 v29, v29, v132
	v_mul_f32_e32 v30, v30, v134
	v_mul_f32_e32 v31, v31, v136
	s_waitcnt lgkmcnt(3)
	v_fmac_f32_e32 v28, v162, v131
	s_waitcnt lgkmcnt(2)
	v_fmac_f32_e32 v29, v163, v133
	s_waitcnt lgkmcnt(1)
	v_fmac_f32_e32 v30, v164, v135
	s_waitcnt lgkmcnt(0)
	v_fmac_f32_e32 v31, v165, v137
	ds_bpermute_b32 v162, v167, v24
	ds_bpermute_b32 v163, v167, v25
	ds_bpermute_b32 v164, v167, v26
	ds_bpermute_b32 v165, v167, v27
	v_mul_f32_e32 v24, v24, v196
	v_mul_f32_e32 v25, v25, v198
	v_mul_f32_e32 v26, v26, v158
	v_mul_f32_e32 v27, v27, v160
	s_waitcnt lgkmcnt(3)
	v_fmac_f32_e32 v24, v162, v197
	s_waitcnt lgkmcnt(2)
	v_fmac_f32_e32 v25, v163, v199
	s_waitcnt lgkmcnt(1)
	v_fmac_f32_e32 v26, v164, v159
	s_waitcnt lgkmcnt(0)
	v_fmac_f32_e32 v27, v165, v161
	s_cmp_lg_u32 s37, 4
	s_cbranch_scc1 .Lepi_rs_6_0
	v_pk_mul_f32 v[28:29], v[28:29], s[2:3]
	v_pk_mul_f32 v[30:31], v[30:31], s[2:3]
	v_pk_mul_f32 v[24:25], v[24:25], s[2:3]
	v_pk_mul_f32 v[26:27], v[26:27], s[2:3]
.Lepi_rs_6_0:
	v_cvt_pk_bf16_f32 v28, v28, v29
	v_cvt_pk_bf16_f32 v29, v30, v31
	v_cvt_pk_bf16_f32 v30, v24, v25
	v_cvt_pk_bf16_f32 v31, v26, v27
	global_store_dwordx4 v157, v[28:31], s[8:9]
	ds_bpermute_b32 v162, v167, v20
	ds_bpermute_b32 v163, v167, v21
	ds_bpermute_b32 v164, v167, v22
	ds_bpermute_b32 v165, v167, v23
	v_mul_f32_e32 v20, v20, v130
	v_mul_f32_e32 v21, v21, v132
	v_mul_f32_e32 v22, v22, v134
	v_mul_f32_e32 v23, v23, v136
	s_waitcnt lgkmcnt(3)
	v_fmac_f32_e32 v20, v162, v131
	s_waitcnt lgkmcnt(2)
	v_fmac_f32_e32 v21, v163, v133
	s_waitcnt lgkmcnt(1)
	v_fmac_f32_e32 v22, v164, v135
	s_waitcnt lgkmcnt(0)
	v_fmac_f32_e32 v23, v165, v137
	ds_bpermute_b32 v162, v167, v16
	ds_bpermute_b32 v163, v167, v17
	ds_bpermute_b32 v164, v167, v18
	ds_bpermute_b32 v165, v167, v19
	v_mul_f32_e32 v16, v16, v196
	v_mul_f32_e32 v17, v17, v198
	v_mul_f32_e32 v18, v18, v158
	v_mul_f32_e32 v19, v19, v160
	s_waitcnt lgkmcnt(3)
	v_fmac_f32_e32 v16, v162, v197
	s_waitcnt lgkmcnt(2)
	v_fmac_f32_e32 v17, v163, v199
	s_waitcnt lgkmcnt(1)
	v_fmac_f32_e32 v18, v164, v159
	s_waitcnt lgkmcnt(0)
	v_fmac_f32_e32 v19, v165, v161
	s_cmp_lg_u32 s37, 4
	s_cbranch_scc1 .Lepi_rs_6_1
	v_pk_mul_f32 v[20:21], v[20:21], s[2:3]
	v_pk_mul_f32 v[22:23], v[22:23], s[2:3]
	v_pk_mul_f32 v[16:17], v[16:17], s[2:3]
	v_pk_mul_f32 v[18:19], v[18:19], s[2:3]
.Lepi_rs_6_1:
	v_cvt_pk_bf16_f32 v20, v20, v21
	v_cvt_pk_bf16_f32 v21, v22, v23
	v_cvt_pk_bf16_f32 v22, v16, v17
	v_cvt_pk_bf16_f32 v23, v18, v19
	global_store_dwordx4 v157, v[20:23], s[8:9] offset:256
	v_add_u32_e32 v157, s20, v157
	s_waitcnt vmcnt(2)
	v_mul_f32_e32 v127, v138, v127
	v_mul_f32_e32 v129, v138, v129
	v_mul_f32_e32 v123, v138, v123
	v_mul_f32_e32 v125, v138, v125
	v_mul_f32_e32 v119, v138, v119
	v_mul_f32_e32 v121, v138, v121
	v_mul_f32_e32 v115, v138, v115
	v_mul_f32_e32 v117, v138, v117
	ds_bpermute_b32 v162, v167, v12
	ds_bpermute_b32 v163, v167, v13
	ds_bpermute_b32 v164, v167, v14
	ds_bpermute_b32 v165, v167, v15
	v_mul_f32_e32 v12, v12, v126
	v_mul_f32_e32 v13, v13, v128
	v_mul_f32_e32 v14, v14, v122
	v_mul_f32_e32 v15, v15, v124
	s_waitcnt lgkmcnt(3)
	v_fmac_f32_e32 v12, v162, v127
	s_waitcnt lgkmcnt(2)
	v_fmac_f32_e32 v13, v163, v129
	s_waitcnt lgkmcnt(1)
	v_fmac_f32_e32 v14, v164, v123
	s_waitcnt lgkmcnt(0)
	v_fmac_f32_e32 v15, v165, v125
	ds_bpermute_b32 v162, v167, v8
	ds_bpermute_b32 v163, v167, v9
	ds_bpermute_b32 v164, v167, v10
	ds_bpermute_b32 v165, v167, v11
	v_mul_f32_e32 v8, v8, v118
	v_mul_f32_e32 v9, v9, v120
	v_mul_f32_e32 v10, v10, v114
	v_mul_f32_e32 v11, v11, v116
	s_waitcnt lgkmcnt(3)
	v_fmac_f32_e32 v8, v162, v119
	s_waitcnt lgkmcnt(2)
	v_fmac_f32_e32 v9, v163, v121
	s_waitcnt lgkmcnt(1)
	v_fmac_f32_e32 v10, v164, v115
	s_waitcnt lgkmcnt(0)
	v_fmac_f32_e32 v11, v165, v117
	s_cmp_lg_u32 s37, 4
	s_cbranch_scc1 .Lepi_rs_7_0
	v_pk_mul_f32 v[12:13], v[12:13], s[2:3]
	v_pk_mul_f32 v[14:15], v[14:15], s[2:3]
	v_pk_mul_f32 v[8:9], v[8:9], s[2:3]
	v_pk_mul_f32 v[10:11], v[10:11], s[2:3]
.Lepi_rs_7_0:
	v_cvt_pk_bf16_f32 v12, v12, v13
	v_cvt_pk_bf16_f32 v13, v14, v15
	v_cvt_pk_bf16_f32 v14, v8, v9
	v_cvt_pk_bf16_f32 v15, v10, v11
	global_store_dwordx4 v157, v[12:15], s[8:9]
	ds_bpermute_b32 v162, v167, v4
	ds_bpermute_b32 v163, v167, v5
	ds_bpermute_b32 v164, v167, v6
	ds_bpermute_b32 v165, v167, v7
	v_mul_f32_e32 v4, v4, v126
	v_mul_f32_e32 v5, v5, v128
	v_mul_f32_e32 v6, v6, v122
	v_mul_f32_e32 v7, v7, v124
	s_waitcnt lgkmcnt(3)
	v_fmac_f32_e32 v4, v162, v127
	s_waitcnt lgkmcnt(2)
	v_fmac_f32_e32 v5, v163, v129
	s_waitcnt lgkmcnt(1)
	v_fmac_f32_e32 v6, v164, v123
	s_waitcnt lgkmcnt(0)
	v_fmac_f32_e32 v7, v165, v125
	ds_bpermute_b32 v162, v167, v0
	ds_bpermute_b32 v163, v167, v1
	ds_bpermute_b32 v164, v167, v2
	ds_bpermute_b32 v165, v167, v3
	v_mul_f32_e32 v0, v0, v118
	v_mul_f32_e32 v1, v1, v120
	v_mul_f32_e32 v2, v2, v114
	v_mul_f32_e32 v3, v3, v116
	s_waitcnt lgkmcnt(3)
	v_fmac_f32_e32 v0, v162, v119
	s_waitcnt lgkmcnt(2)
	v_fmac_f32_e32 v1, v163, v121
	s_waitcnt lgkmcnt(1)
	v_fmac_f32_e32 v2, v164, v115
	s_waitcnt lgkmcnt(0)
	v_fmac_f32_e32 v3, v165, v117
	s_cmp_lg_u32 s37, 4
	s_cbranch_scc1 .Lepi_rs_7_1
	v_pk_mul_f32 v[4:5], v[4:5], s[2:3]
	v_pk_mul_f32 v[6:7], v[6:7], s[2:3]
	v_pk_mul_f32 v[0:1], v[0:1], s[2:3]
	v_pk_mul_f32 v[2:3], v[2:3], s[2:3]
.Lepi_rs_7_1:
	v_cvt_pk_bf16_f32 v4, v4, v5
	v_cvt_pk_bf16_f32 v5, v6, v7
	v_cvt_pk_bf16_f32 v6, v0, v1
	v_cvt_pk_bf16_f32 v7, v2, v3
	global_store_dwordx4 v157, v[4:7], s[8:9] offset:256
	s_branch .Lepi_exit
.Lepi_rot_plain:
	s_cmp_lg_u32 s37, 4
	s_cbranch_scc1 .Lepi_copy
	v_pk_mul_f32 v[126:127], v[126:127], s[2:3]
	v_pk_mul_f32 v[128:129], v[128:129], s[2:3]
	v_pk_mul_f32 v[122:123], v[122:123], s[2:3]
	v_pk_mul_f32 v[124:125], v[124:125], s[2:3]
	v_cvt_pk_bf16_f32 v126, v126, v127
	v_cvt_pk_bf16_f32 v127, v128, v129
	v_cvt_pk_bf16_f32 v128, v122, v123
	v_cvt_pk_bf16_f32 v129, v124, v125
	global_store_dwordx4 v157, v[126:129], s[8:9]
	v_pk_mul_f32 v[118:119], v[118:119], s[2:3]
	v_pk_mul_f32 v[120:121], v[120:121], s[2:3]
	v_pk_mul_f32 v[114:115], v[114:115], s[2:3]
	v_pk_mul_f32 v[116:117], v[116:117], s[2:3]
	v_cvt_pk_bf16_f32 v118, v118, v119
	v_cvt_pk_bf16_f32 v119, v120, v121
	v_cvt_pk_bf16_f32 v120, v114, v115
	v_cvt_pk_bf16_f32 v121, v116, v117
	global_store_dwordx4 v157, v[118:121], s[8:9] offset:256
	v_add_u32_e32 v157, s20, v157
	v_pk_mul_f32 v[110:111], v[110:111], s[2:3]
	v_pk_mul_f32 v[112:113], v[112:113], s[2:3]
	v_pk_mul_f32 v[106:107], v[106:107], s[2:3]
	v_pk_mul_f32 v[108:109], v[108:109], s[2:3]
	v_cvt_pk_bf16_f32 v110, v110, v111
	v_cvt_pk_bf16_f32 v111, v112, v113
	v_cvt_pk_bf16_f32 v112, v106, v107
	v_cvt_pk_bf16_f32 v113, v108, v109
	global_store_dwordx4 v157, v[110:113], s[8:9]
	v_pk_mul_f32 v[102:103], v[102:103], s[2:3]
	v_pk_mul_f32 v[104:105], v[104:105], s[2:3]
	v_pk_mul_f32 v[98:99], v[98:99], s[2:3]
	v_pk_mul_f32 v[100:101], v[100:101], s[2:3]
	v_cvt_pk_bf16_f32 v102, v102, v103
	v_cvt_pk_bf16_f32 v103, v104, v105
	v_cvt_pk_bf16_f32 v104, v98, v99
	v_cvt_pk_bf16_f32 v105, v100, v101
	global_store_dwordx4 v157, v[102:105], s[8:9] offset:256
	v_add_u32_e32 v157, s20, v157
	v_pk_mul_f32 v[94:95], v[94:95], s[2:3]
	v_pk_mul_f32 v[96:97], v[96:97], s[2:3]
	v_pk_mul_f32 v[90:91], v[90:91], s[2:3]
	v_pk_mul_f32 v[92:93], v[92:93], s[2:3]
	v_cvt_pk_bf16_f32 v94, v94, v95
	v_cvt_pk_bf16_f32 v95, v96, v97
	v_cvt_pk_bf16_f32 v96, v90, v91
	v_cvt_pk_bf16_f32 v97, v92, v93
	global_store_dwordx4 v157, v[94:97], s[8:9]
	v_pk_mul_f32 v[86:87], v[86:87], s[2:3]
	v_pk_mul_f32 v[88:89], v[88:89], s[2:3]
	v_pk_mul_f32 v[82:83], v[82:83], s[2:3]
	v_pk_mul_f32 v[84:85], v[84:85], s[2:3]
	v_cvt_pk_bf16_f32 v86, v86, v87
	v_cvt_pk_bf16_f32 v87, v88, v89
	v_cvt_pk_bf16_f32 v88, v82, v83
	v_cvt_pk_bf16_f32 v89, v84, v85
	global_store_dwordx4 v157, v[86:89], s[8:9] offset:256
	v_add_u32_e32 v157, s20, v157
	v_pk_mul_f32 v[78:79], v[78:79], s[2:3]
	v_pk_mul_f32 v[80:81], v[80:81], s[2:3]
	v_pk_mul_f32 v[74:75], v[74:75], s[2:3]
	v_pk_mul_f32 v[76:77], v[76:77], s[2:3]
	v_cvt_pk_bf16_f32 v78, v78, v79
	v_cvt_pk_bf16_f32 v79, v80, v81
	v_cvt_pk_bf16_f32 v80, v74, v75
	v_cvt_pk_bf16_f32 v81, v76, v77
	global_store_dwordx4 v157, v[78:81], s[8:9]
	v_pk_mul_f32 v[70:71], v[70:71], s[2:3]
	v_pk_mul_f32 v[72:73], v[72:73], s[2:3]
	v_pk_mul_f32 v[66:67], v[66:67], s[2:3]
	v_pk_mul_f32 v[68:69], v[68:69], s[2:3]
	v_cvt_pk_bf16_f32 v70, v70, v71
	v_cvt_pk_bf16_f32 v71, v72, v73
	v_cvt_pk_bf16_f32 v72, v66, v67
	v_cvt_pk_bf16_f32 v73, v68, v69
	global_store_dwordx4 v157, v[70:73], s[8:9] offset:256
	v_add_u32_e32 v157, s36, v157
	v_pk_mul_f32 v[60:61], v[60:61], s[2:3]
	v_pk_mul_f32 v[62:63], v[62:63], s[2:3]
	v_pk_mul_f32 v[56:57], v[56:57], s[2:3]
	v_pk_mul_f32 v[58:59], v[58:59], s[2:3]
	v_cvt_pk_bf16_f32 v60, v60, v61
	v_cvt_pk_bf16_f32 v61, v62, v63
	v_cvt_pk_bf16_f32 v62, v56, v57
	v_cvt_pk_bf16_f32 v63, v58, v59
	global_store_dwordx4 v157, v[60:63], s[8:9]
	v_pk_mul_f32 v[52:53], v[52:53], s[2:3]
	v_pk_mul_f32 v[54:55], v[54:55], s[2:3]
	v_pk_mul_f32 v[48:49], v[48:49], s[2:3]
	v_pk_mul_f32 v[50:51], v[50:51], s[2:3]
	v_cvt_pk_bf16_f32 v52, v52, v53
	v_cvt_pk_bf16_f32 v53, v54, v55
	v_cvt_pk_bf16_f32 v54, v48, v49
	v_cvt_pk_bf16_f32 v55, v50, v51
	global_store_dwordx4 v157, v[52:55], s[8:9] offset:256
	v_add_u32_e32 v157, s20, v157
	v_pk_mul_f32 v[44:45], v[44:45], s[2:3]
	v_pk_mul_f32 v[46:47], v[46:47], s[2:3]
	v_pk_mul_f32 v[40:41], v[40:41], s[2:3]
	v_pk_mul_f32 v[42:43], v[42:43], s[2:3]
	v_cvt_pk_bf16_f32 v44, v44, v45
	v_cvt_pk_bf16_f32 v45, v46, v47
	v_cvt_pk_bf16_f32 v46, v40, v41
	v_cvt_pk_bf16_f32 v47, v42, v43
	global_store_dwordx4 v157, v[44:47], s[8:9]
	v_pk_mul_f32 v[36:37], v[36:37], s[2:3]
	v_pk_mul_f32 v[38:39], v[38:39], s[2:3]
	v_pk_mul_f32 v[32:33], v[32:33], s[2:3]
	v_pk_mul_f32 v[34:35], v[34:35], s[2:3]
	v_cvt_pk_bf16_f32 v36, v36, v37
	v_cvt_pk_bf16_f32 v37, v38, v39
	v_cvt_pk_bf16_f32 v38, v32, v33
	v_cvt_pk_bf16_f32 v39, v34, v35
	global_store_dwordx4 v157, v[36:39], s[8:9] offset:256
	v_add_u32_e32 v157, s20, v157
	v_pk_mul_f32 v[28:29], v[28:29], s[2:3]
	v_pk_mul_f32 v[30:31], v[30:31], s[2:3]
	v_pk_mul_f32 v[24:25], v[24:25], s[2:3]
	v_pk_mul_f32 v[26:27], v[26:27], s[2:3]
	v_cvt_pk_bf16_f32 v28, v28, v29
	v_cvt_pk_bf16_f32 v29, v30, v31
	v_cvt_pk_bf16_f32 v30, v24, v25
	v_cvt_pk_bf16_f32 v31, v26, v27
	global_store_dwordx4 v157, v[28:31], s[8:9]
	v_pk_mul_f32 v[20:21], v[20:21], s[2:3]
	v_pk_mul_f32 v[22:23], v[22:23], s[2:3]
	v_pk_mul_f32 v[16:17], v[16:17], s[2:3]
	v_pk_mul_f32 v[18:19], v[18:19], s[2:3]
	v_cvt_pk_bf16_f32 v20, v20, v21
	v_cvt_pk_bf16_f32 v21, v22, v23
	v_cvt_pk_bf16_f32 v22, v16, v17
	v_cvt_pk_bf16_f32 v23, v18, v19
	global_store_dwordx4 v157, v[20:23], s[8:9] offset:256
	v_add_u32_e32 v157, s20, v157
	v_pk_mul_f32 v[12:13], v[12:13], s[2:3]
	v_pk_mul_f32 v[14:15], v[14:15], s[2:3]
	v_pk_mul_f32 v[8:9], v[8:9], s[2:3]
	v_pk_mul_f32 v[10:11], v[10:11], s[2:3]
	v_cvt_pk_bf16_f32 v12, v12, v13
	v_cvt_pk_bf16_f32 v13, v14, v15
	v_cvt_pk_bf16_f32 v14, v8, v9
	v_cvt_pk_bf16_f32 v15, v10, v11
	global_store_dwordx4 v157, v[12:15], s[8:9]
	v_pk_mul_f32 v[4:5], v[4:5], s[2:3]
	v_pk_mul_f32 v[6:7], v[6:7], s[2:3]
	v_pk_mul_f32 v[0:1], v[0:1], s[2:3]
	v_pk_mul_f32 v[2:3], v[2:3], s[2:3]
	v_cvt_pk_bf16_f32 v4, v4, v5
	v_cvt_pk_bf16_f32 v5, v6, v7
	v_cvt_pk_bf16_f32 v6, v0, v1
	v_cvt_pk_bf16_f32 v7, v2, v3
	global_store_dwordx4 v157, v[4:7], s[8:9] offset:256
	s_branch .Lepi_exit
